# resid epilogue: gate reload chain of boundary-straddling tiles issues all loads before one wait (was ten dependent round trips)
# speedup vs baseline: 1.0031x; 1.0031x over previous
.LBB0_898:
	s_movk_i32 s4, 0x1fdf
	v_mov_b64_e32 v[166:167], v[186:187]
	v_mov_b64_e32 v[174:175], v[194:195]
	s_and_b64 vcc, exec, s[0:1]
	v_cmp_lt_i32_e64 s[4:5], s4, v249
	v_mov_b64_e32 v[168:169], v[188:189]
	v_mov_b64_e32 v[176:177], v[196:197]
	s_cbranch_vccnz .LBB0_900
	s_add_i32 s15, s14, 0xffffe020
	s_lshr_b32 s15, s15, 10
	s_mulk_i32 s15, 0x1800
	s_addk_i32 s15, 0x1800
	v_mov_b32_e32 v0, s15
	v_cndmask_b32_e64 v0, 0, v0, s[4:5]
	v_lshl_add_u64 v[106:107], v[0:1], 2, s[12:13]
	v_lshl_add_u64 v[106:107], v[242:243], 2, v[106:107]
	flat_load_dwordx4 v[174:177], v[106:107]
	flat_load_dwordx4 v[166:169], v[106:107] offset:16
.LBB0_900:
	s_movk_i32 s4, 0x1f9f
	v_mov_b64_e32 v[146:147], v[166:167]
	v_mov_b64_e32 v[150:151], v[174:175]
	s_and_b64 vcc, exec, s[0:1]
	v_cmp_lt_i32_e64 s[4:5], s4, v249
	v_mov_b64_e32 v[148:149], v[168:169]
	v_mov_b64_e32 v[152:153], v[176:177]
	s_cbranch_vccnz .LBB0_902
	s_add_i32 s15, s14, 0xffffe060
	s_lshr_b32 s15, s15, 10
	s_mulk_i32 s15, 0x1800
	s_addk_i32 s15, 0x1800
	v_mov_b32_e32 v0, s15
	v_cndmask_b32_e64 v0, 0, v0, s[4:5]
	v_lshl_add_u64 v[106:107], v[0:1], 2, s[12:13]
	v_lshl_add_u64 v[106:107], v[242:243], 2, v[106:107]
	flat_load_dwordx4 v[150:153], v[106:107]
	flat_load_dwordx4 v[146:149], v[106:107] offset:16
.LBB0_902:
	s_movk_i32 s4, 0x1f8f
	v_mov_b64_e32 v[122:123], v[146:147]
	v_mov_b64_e32 v[126:127], v[150:151]
	s_and_b64 vcc, exec, s[0:1]
	v_cmp_lt_i32_e64 s[4:5], s4, v249
	v_mov_b64_e32 v[124:125], v[148:149]
	v_mov_b64_e32 v[128:129], v[152:153]
	s_cbranch_vccnz .LBB0_904
	s_add_i32 s15, s14, 0xffffe070
	s_lshr_b32 s15, s15, 10
	s_mulk_i32 s15, 0x1800
	s_addk_i32 s15, 0x1800
	v_mov_b32_e32 v0, s15
	v_cndmask_b32_e64 v0, 0, v0, s[4:5]
	v_lshl_add_u64 v[106:107], v[0:1], 2, s[12:13]
	v_lshl_add_u64 v[106:107], v[242:243], 2, v[106:107]
	flat_load_dwordx4 v[126:129], v[106:107]
	flat_load_dwordx4 v[122:125], v[106:107] offset:16
.LBB0_904:
	s_movk_i32 s4, 0x1f7f
	v_mov_b64_e32 v[106:107], v[122:123]
	v_mov_b64_e32 v[110:111], v[126:127]
	s_and_b64 vcc, exec, s[0:1]
	v_cmp_lt_i32_e64 s[4:5], s4, v249
	v_mov_b64_e32 v[108:109], v[124:125]
	v_mov_b64_e32 v[112:113], v[128:129]
	s_cbranch_vccnz .LBB0_906
	s_add_i32 s15, s14, 0xffffe080
	s_lshr_b32 s15, s15, 10
	s_mulk_i32 s15, 0x1800
	s_addk_i32 s15, 0x1800
	v_mov_b32_e32 v0, s15
	v_cndmask_b32_e64 v0, 0, v0, s[4:5]
	v_lshl_add_u64 v[106:107], v[0:1], 2, s[12:13]
	v_lshl_add_u64 v[106:107], v[242:243], 2, v[106:107]
	flat_load_dwordx4 v[110:113], v[106:107]
	s_nop 0
	flat_load_dwordx4 v[106:109], v[106:107] offset:16

.LBB0_908:
	v_lshl_add_u64 v[130:131], v[130:131], 2, s[12:13]
	v_lshl_add_u64 v[130:131], v[242:243], 2, v[130:131]
	v_mov_b64_e32 v[234:235], v[206:207]
	v_mov_b64_e32 v[236:237], v[208:209]
	v_mov_b64_e32 v[238:239], v[244:245]
	v_mov_b64_e32 v[240:241], v[250:251]
	s_and_b64 vcc, exec, s[0:1]
	v_mov_b64_e32 v[222:223], v[234:235]
	v_mov_b64_e32 v[226:227], v[238:239]
	v_mov_b64_e32 v[224:225], v[236:237]
	v_mov_b64_e32 v[228:229], v[240:241]
	s_cbranch_vccnz .LBB0_910
	s_add_i32 s4, s14, 0xffffe010
	s_lshr_b32 s4, s4, 10
	s_mulk_i32 s4, 0x1800
	s_addk_i32 s4, 0x1800
	v_mov_b32_e32 v0, s4
	s_movk_i32 s4, 0x1fef
	v_cmp_lt_i32_e32 vcc, s4, v249
	s_nop 1
	v_cndmask_b32_e32 v0, 0, v0, vcc
	v_lshl_add_u64 v[130:131], v[0:1], 2, s[12:13]
	v_lshl_add_u64 v[130:131], v[242:243], 2, v[130:131]
	flat_load_dwordx4 v[226:229], v[130:131] offset:512
	flat_load_dwordx4 v[222:225], v[130:131] offset:528
.LBB0_910:
	v_mov_b64_e32 v[202:203], v[222:223]
	v_mov_b64_e32 v[206:207], v[226:227]
	s_and_b64 vcc, exec, s[0:1]
	v_mov_b64_e32 v[204:205], v[224:225]
	v_mov_b64_e32 v[208:209], v[228:229]
	s_cbranch_vccnz .LBB0_912
	s_add_i32 s4, s14, 0xffffe020
	s_lshr_b32 s4, s4, 10
	s_mulk_i32 s4, 0x1800
	s_addk_i32 s4, 0x1800
	v_mov_b32_e32 v0, s4
	s_movk_i32 s4, 0x1fdf
	v_cmp_lt_i32_e32 vcc, s4, v249
	s_nop 1
	v_cndmask_b32_e32 v0, 0, v0, vcc
	v_lshl_add_u64 v[130:131], v[0:1], 2, s[12:13]
	v_lshl_add_u64 v[130:131], v[242:243], 2, v[130:131]
	flat_load_dwordx4 v[206:209], v[130:131] offset:512
	flat_load_dwordx4 v[202:205], v[130:131] offset:528
.LBB0_912:
	v_mov_b64_e32 v[178:179], v[202:203]
	v_mov_b64_e32 v[182:183], v[206:207]
	s_and_b64 vcc, exec, s[0:1]
	v_mov_b64_e32 v[180:181], v[204:205]
	v_mov_b64_e32 v[184:185], v[208:209]
	s_cbranch_vccnz .LBB0_914
	s_add_i32 s4, s14, 0xffffe060
	s_lshr_b32 s4, s4, 10
	s_mulk_i32 s4, 0x1800
	s_addk_i32 s4, 0x1800
	v_mov_b32_e32 v0, s4
	s_movk_i32 s4, 0x1f9f
	v_cmp_lt_i32_e32 vcc, s4, v249
	s_nop 1
	v_cndmask_b32_e32 v0, 0, v0, vcc
	v_lshl_add_u64 v[130:131], v[0:1], 2, s[12:13]
	v_lshl_add_u64 v[130:131], v[242:243], 2, v[130:131]
	flat_load_dwordx4 v[182:185], v[130:131] offset:512
	flat_load_dwordx4 v[178:181], v[130:131] offset:528
.LBB0_914:
	v_mov_b64_e32 v[154:155], v[178:179]
	v_mov_b64_e32 v[158:159], v[182:183]
	s_and_b64 vcc, exec, s[0:1]
	v_mov_b64_e32 v[156:157], v[180:181]
	v_mov_b64_e32 v[160:161], v[184:185]
	s_cbranch_vccnz .LBB0_916
	s_add_i32 s4, s14, 0xffffe070
	s_lshr_b32 s4, s4, 10
	s_mulk_i32 s4, 0x1800
	s_addk_i32 s4, 0x1800
	v_mov_b32_e32 v0, s4
	s_movk_i32 s4, 0x1f8f
	v_cmp_lt_i32_e32 vcc, s4, v249
	s_nop 1
	v_cndmask_b32_e32 v0, 0, v0, vcc
	v_lshl_add_u64 v[130:131], v[0:1], 2, s[12:13]
	v_lshl_add_u64 v[130:131], v[242:243], 2, v[130:131]
	flat_load_dwordx4 v[158:161], v[130:131] offset:512
	flat_load_dwordx4 v[154:157], v[130:131] offset:528
.LBB0_916:
	v_mov_b64_e32 v[130:131], v[154:155]
	v_mov_b64_e32 v[134:135], v[158:159]
	v_mov_b32_e32 v248, 1
	s_and_b64 vcc, exec, s[0:1]
	v_mov_b64_e32 v[132:133], v[156:157]
	v_mov_b64_e32 v[136:137], v[160:161]
	s_cbranch_vccnz .LBB0_918
	s_addk_i32 s14, 0xe080
	s_lshr_b32 s4, s14, 10
	s_mulk_i32 s4, 0x1800
	s_addk_i32 s4, 0x1800
	v_mov_b32_e32 v0, s4
	s_movk_i32 s4, 0x1f7f
	v_cmp_lt_i32_e32 vcc, s4, v249
	s_nop 1
	v_cndmask_b32_e32 v0, 0, v0, vcc
	v_lshl_add_u64 v[130:131], v[0:1], 2, s[12:13]
	v_lshl_add_u64 v[130:131], v[242:243], 2, v[130:131]
	flat_load_dwordx4 v[134:137], v[130:131] offset:512
	s_nop 0
	flat_load_dwordx4 v[130:133], v[130:131] offset:528
.LBB0_918:
	s_waitcnt vmcnt(0) lgkmcnt(0)
	v_lshlrev_b32_e32 v250, 16, v230
	v_and_b32_e32 v251, 0xffff0000, v230
	v_lshlrev_b32_e32 v230, 16, v231
	v_and_b32_e32 v231, 0xffff0000, v231
	v_lshlrev_b32_e32 v244, 16, v232
	v_and_b32_e32 v245, 0xffff0000, v232
	v_lshlrev_b32_e32 v232, 16, v233
	v_and_b32_e32 v233, 0xffff0000, v233
	v_pk_mul_f32 v[92:93], v[92:93], v[240:241]
	s_mov_b32 s4, 0x3fd744fd
	v_pk_mul_f32 v[84:85], v[84:85], v[236:237]
	v_pk_mul_f32 v[82:83], v[82:83], v[234:235]
	v_pk_mul_f32 v[90:91], v[90:91], v[238:239]
	v_pk_fma_f32 v[238:239], v[230:231], s[4:5], v[92:93] op_sel_hi:[1,0,1]
	v_pk_fma_f32 v[230:231], v[232:233], s[4:5], v[84:85] op_sel_hi:[1,0,1]
	v_pk_fma_f32 v[232:233], v[244:245], s[4:5], v[82:83] op_sel_hi:[1,0,1]
	v_lshlrev_b32_e32 v82, 16, v190
	v_and_b32_e32 v83, 0xffff0000, v190
	v_lshlrev_b32_e32 v84, 16, v191
	v_and_b32_e32 v85, 0xffff0000, v191
	v_pk_mul_f32 v[96:97], v[96:97], v[216:217]
	v_pk_mul_f32 v[94:95], v[94:95], v[214:215]
	v_pk_fma_f32 v[240:241], v[250:251], s[4:5], v[90:91] op_sel_hi:[1,0,1]
	v_lshlrev_b32_e32 v90, 16, v192
	v_and_b32_e32 v91, 0xffff0000, v192
	v_lshlrev_b32_e32 v92, 16, v193
	v_and_b32_e32 v93, 0xffff0000, v193
	v_pk_fma_f32 v[214:215], v[84:85], s[4:5], v[96:97] op_sel_hi:[1,0,1]
	v_pk_fma_f32 v[216:217], v[82:83], s[4:5], v[94:95] op_sel_hi:[1,0,1]
	v_pk_mul_f32 v[82:83], v[88:89], v[212:213]
	v_pk_mul_f32 v[84:85], v[86:87], v[210:211]
	v_pk_fma_f32 v[210:211], v[92:93], s[4:5], v[82:83] op_sel_hi:[1,0,1]
	v_pk_fma_f32 v[212:213], v[90:91], s[4:5], v[84:85] op_sel_hi:[1,0,1]
	v_pk_mov_b32 v[82:83], v[216:217], v[214:215] op_sel:[1,0]
	v_mov_b32_e32 v84, v216
	v_mov_b32_e32 v85, v215
	v_pk_add_f32 v[82:83], v[82:83], v[84:85]
	v_pk_mov_b32 v[84:85], v[212:213], v[210:211] op_sel:[1,0]
	v_mov_b32_e32 v86, v212
	v_mov_b32_e32 v87, v211
	v_pk_add_f32 v[84:85], v[84:85], v[86:87]
	v_add_f32_e32 v82, v82, v83
	v_pk_add_f32 v[84:85], v[84:85], v[84:85] op_sel:[0,1] op_sel_hi:[1,0]
	v_add_f32_e32 v82, 0, v82
	v_add_f32_e32 v86, v240, v241
	v_add_f32_e32 v88, v238, v239
	v_mov_b32_e32 v83, v232
	v_mov_b32_e32 v85, v233
	v_mov_b32_e32 v87, v230
	v_mov_b32_e32 v89, v231
	v_and_b32_e32 v0, 63, v252
	v_pk_add_f32 v[82:83], v[82:83], v[84:85]
	v_pk_add_f32 v[84:85], v[86:87], v[88:89]
	v_lshlrev_b32_e32 v90, 2, v0
	v_pk_add_f32 v[82:83], v[82:83], v[84:85]
	v_xor_b32_e32 v234, 64, v90
	v_add_f32_e32 v82, v82, v83
	v_mov_b32_e32 v83, v82
	s_nop 1
	v_permlane16_swap_b32_e32 v82, v83
	v_xor_b32_e32 v235, 0x80, v90
	v_readlane_b32 s4, v254, 11
	v_cmp_gt_u32_e32 vcc, 16, v0
	s_waitcnt lgkmcnt(0)
	v_add_f32_e32 v82, v82, v83
	v_mov_b32_e32 v83, v82
	s_nop 1
	v_permlane32_swap_b32_e32 v82, v83
	v_or_b32_e32 v236, s4, v253
	v_readlane_b32 s4, v254, 6
	s_waitcnt lgkmcnt(0)
	v_add_f32_e32 v83, v82, v83
	v_fmamk_f32 v84, v83, 0xbc800000, v215
	v_fmamk_f32 v86, v83, 0xbc800000, v217
	v_fmamk_f32 v82, v83, 0xbc800000, v214
	v_fmamk_f32 v85, v83, 0xbc800000, v216
	v_mul_f32_e32 v86, v86, v86
	v_mul_f32_e32 v84, v84, v84
	v_fmac_f32_e32 v86, v85, v85
	v_fmac_f32_e32 v84, v82, v82
	v_fmamk_f32 v85, v83, 0xbc800000, v211
	v_fmamk_f32 v87, v83, 0xbc800000, v213
	v_add_f32_e32 v82, v86, v84
	v_fmamk_f32 v84, v83, 0xbc800000, v210
	v_fmamk_f32 v86, v83, 0xbc800000, v212
	v_mul_f32_e32 v87, v87, v87
	v_mul_f32_e32 v85, v85, v85
	v_fmac_f32_e32 v87, v86, v86
	v_fmac_f32_e32 v85, v84, v84
	v_add_f32_e32 v84, v87, v85
	v_fmamk_f32 v85, v83, 0xbc800000, v239
	v_fmamk_f32 v87, v83, 0xbc800000, v241
	v_add_f32_e32 v82, v82, v84
	v_fmamk_f32 v84, v83, 0xbc800000, v238
	v_fmamk_f32 v86, v83, 0xbc800000, v240
	v_mul_f32_e32 v87, v87, v87
	v_mul_f32_e32 v85, v85, v85
	v_fmac_f32_e32 v87, v86, v86
	v_fmac_f32_e32 v85, v84, v84
	v_add_f32_e32 v84, v87, v85
	v_fmamk_f32 v85, v83, 0xbc800000, v231
	v_fmamk_f32 v87, v83, 0xbc800000, v233
	v_add_f32_e32 v82, v84, v82
	v_fmamk_f32 v84, v83, 0xbc800000, v230
	v_fmamk_f32 v86, v83, 0xbc800000, v232
	v_mul_f32_e32 v87, v87, v87
	v_mul_f32_e32 v85, v85, v85
	v_fmac_f32_e32 v87, v86, v86
	v_fmac_f32_e32 v85, v84, v84
	v_add_f32_e32 v84, v87, v85
	v_add_f32_e32 v82, v84, v82
	v_mov_b32_e32 v84, v82
	s_nop 1
	v_permlane16_swap_b32_e32 v82, v84
	s_waitcnt lgkmcnt(0)
	v_add_f32_e32 v84, v82, v84
	v_mov_b32_e32 v85, v84
	s_nop 1
	v_permlane32_swap_b32_e32 v84, v85
	v_lshl_add_u32 v82, v236, 5, s4
	s_and_saveexec_b64 s[4:5], vcc
	s_cbranch_execz .LBB0_920
	v_mul_f32_e32 v86, 0x3c800000, v83
	s_waitcnt lgkmcnt(0)
	v_add_f32_e32 v87, v84, v85
	ds_write_b64 v82, v[86:87]
